# grid barrier: non-leader workgroups poll the top-level generation word directly instead of waiting for their XCD leader to republish it (one hop less per barrier)
# baseline (speedup 1.0000x reference)
.LBB0_824:
	s_or_b64 exec, exec, s[26:27]
	v_cvt_f32_u32_e32 v4, v2
	s_waitcnt vmcnt(0)
	v_readfirstlane_b32 s6, v3
	v_sub_u32_e32 v3, 0, v2
	v_rcp_iflag_f32_e32 v4, v4
	v_add_u32_e32 v5, s6, v1
	v_mul_f32_e32 v4, 0x4f7ffffe, v4
	v_cvt_u32_f32_e32 v4, v4
	v_mul_lo_u32 v1, v3, v4
	v_mul_hi_u32 v1, v4, v1
	v_add_u32_e32 v1, v4, v1
	v_mul_hi_u32 v1, v5, v1
	v_mul_lo_u32 v3, v1, v2
	v_sub_u32_e32 v3, v5, v3
	v_add_u32_e32 v4, 1, v1
	v_cmp_ge_u32_e32 vcc, v3, v2
	s_nop 1
	v_cndmask_b32_e32 v1, v1, v4, vcc
	v_sub_u32_e32 v4, v3, v2
	v_cndmask_b32_e32 v3, v3, v4, vcc
	v_add_u32_e32 v4, 1, v1
	v_cmp_ge_u32_e32 vcc, v3, v2
	v_add_u32_e32 v3, 1, v5
	s_nop 0
	v_cndmask_b32_e32 v1, v1, v4, vcc
	v_mul_lo_u32 v4, v2, v1
	v_add_u32_e32 v2, v4, v2
	v_cmp_ne_u32_e32 vcc, v3, v2
	s_and_saveexec_b64 s[10:11], vcc
	s_xor_b64 s[26:27], exec, s[10:11]
	s_cbranch_execz .LBB0_838
	v_readlane_b32 s10, v253, 43
	v_readlane_b32 s11, v253, 44
	s_waitcnt lgkmcnt(0)
	s_nop 3
	global_load_dword v0, v141, s[10:11] sc1
	s_waitcnt vmcnt(0)
	v_cmp_eq_u32_e32 vcc, v0, v1
	s_and_saveexec_b64 s[28:29], vcc
	s_cbranch_execz .LBB0_837
	s_mov_b32 s6, 1
	s_mov_b64 s[30:31], 0
	s_branch .LBB0_828

.LBB0_832:
	v_readlane_b32 s10, v253, 43
	v_readlane_b32 s11, v253, 44
	s_add_i32 s6, s6, 1
	s_mov_b64 s[42:43], -1
	s_nop 2
	global_load_dword v0, v141, s[10:11] sc1
	s_waitcnt vmcnt(0)
	v_cmp_ne_u32_e32 vcc, v0, v1
	s_orn2_b64 s[38:39], vcc, exec
	s_branch .LBB0_827
